# v29 plus the 384 packed fp32 ops (rotary, q-scale) of the two in-projection GEMM epilogues split into scalar ops
# baseline (speedup 1.0000x reference)
.LBB0_139:
	s_andn2_b64 vcc, exec, s[4:5]
	s_cbranch_vccnz .LBB0_141
	s_waitcnt vmcnt(0)
	v_mul_f32_e32 v160, v122, v133
	v_mul_f32_e32 v162, v122, v132
	v_mov_b32_e32 v122, v127
	v_mov_b32_e32 v154, v129
	v_mov_b32_e32 v155, v131
	v_mul_f32_e32 v158, v126, v132
	v_mul_f32_e32 v168, v126, v133
	v_mul_f32_e32 v170, v122, v134
	v_mul_f32_e32 v171, v123, v135
	v_mov_b32_e32 v126, v123
	v_mov_b32_e32 v152, v128
	v_mov_b32_e32 v153, v130
	v_mul_f32_e32 v156, v120, v154
	v_mul_f32_e32 v157, v121, v155
	v_mov_b32_e32 v159, v170
	v_mov_b32_e32 v161, v171
	v_mul_f32_e32 v122, v126, v134
	v_mul_f32_e32 v123, v127, v135
	v_mul_f32_e32 v120, v120, v152
	v_mul_f32_e32 v121, v121, v153
	v_fma_f32 v152, v124, v152, -v156
	v_fma_f32 v153, v125, v153, -v157
	v_sub_f32_e32 v156, v158, v160
	v_sub_f32_e32 v157, v159, v161
	v_mov_b32_e32 v169, v123
	v_mov_b32_e32 v163, v122
	v_fma_f32 v120, v124, v154, v120
	v_fma_f32 v121, v125, v155, v121
	v_add_f32_e32 v122, v168, v162
	v_add_f32_e32 v123, v169, v163
	v_mov_b32_e32 v124, v152
	v_mov_b32_e32 v125, v153
	v_mov_b32_e32 v126, v156
	v_mov_b32_e32 v127, v157

.LBB0_163:
	s_andn2_b64 vcc, exec, s[26:27]
	v_lshl_add_u64 v[144:145], s[30:31], 0, v[144:145]
	s_cbranch_vccnz .LBB0_165
	s_ashr_i32 s9, s8, 31
	s_mov_b32 s2, 0x3e38aa3b
	v_lshl_add_u64 v[154:155], s[8:9], 1, v[144:145]
	v_mov_b32_e32 v141, 0
	v_mul_f32_e32 v126, s2, v126
	v_mul_f32_e32 v127, s2, v127
	v_mul_f32_e32 v124, s2, v124
	v_mul_f32_e32 v125, s2, v125
	v_mul_f32_e32 v122, s2, v122
	v_mul_f32_e32 v123, s2, v123
	v_mul_f32_e32 v120, s2, v120
	v_mul_f32_e32 v121, s2, v121
	v_lshl_add_u64 v[154:155], v[154:155], 0, v[140:141]
	s_mov_b32 s2, 0x4400000
	s_mov_b64 s[8:9], 0x4400000
	v_cvt_pk_bf16_f32 v124, v124, v125
	v_cvt_pk_bf16_f32 v125, v126, v127
	v_add_co_u32_e32 v126, vcc, s2, v154
	v_lshl_add_u64 v[156:157], v[154:155], 0, s[8:9]
	s_nop 0
	v_addc_co_u32_e32 v127, vcc, 0, v155, vcc
	v_cvt_pk_bf16_f32 v120, v120, v121
	v_cvt_pk_bf16_f32 v121, v122, v123
	global_store_dwordx2 v[126:127], v[124:125], off
	global_store_dwordx2 v[156:157], v[120:121], off offset:64
.LBB0_165:
	s_or_b32 s2, s35, 0x80000001
	s_cmp_lt_u32 s2, 0x8000000b
	s_cselect_b64 s[8:9], -1, 0
	s_cmp_gt_u32 s2, 0x8000000a
	s_cbranch_scc1 .LBB0_167
	s_waitcnt vmcnt(0)
	v_mov_b32_e32 v120, v128
	v_mul_f32_e32 v126, v114, v133
	v_mul_f32_e32 v128, v114, v132
	v_mov_b32_e32 v114, v119
	v_mov_b32_e32 v121, v130
	v_mov_b32_e32 v130, v129
	v_mul_f32_e32 v124, v118, v132
	v_mul_f32_e32 v132, v118, v133
	v_mul_f32_e32 v154, v114, v134
	v_mul_f32_e32 v155, v115, v135
	v_mov_b32_e32 v118, v115
	v_mul_f32_e32 v122, v112, v130
	v_mul_f32_e32 v123, v113, v131
	v_mov_b32_e32 v125, v154
	v_mov_b32_e32 v127, v155
	v_mul_f32_e32 v114, v118, v134
	v_mul_f32_e32 v115, v119, v135
	v_mul_f32_e32 v112, v112, v120
	v_mul_f32_e32 v113, v113, v121
	v_fma_f32 v120, v116, v120, -v122
	v_fma_f32 v121, v117, v121, -v123
	v_sub_f32_e32 v122, v124, v126
	v_sub_f32_e32 v123, v125, v127
	v_mov_b32_e32 v133, v115
	v_mov_b32_e32 v129, v114
	v_fma_f32 v112, v116, v130, v112
	v_fma_f32 v113, v117, v131, v113
	v_add_f32_e32 v114, v132, v128
	v_add_f32_e32 v115, v133, v129
	v_mov_b32_e32 v116, v120
	v_mov_b32_e32 v117, v121
	v_mov_b32_e32 v118, v122
	v_mov_b32_e32 v119, v123

.LBB0_174:
	s_ashr_i32 s7, s6, 31
	s_mov_b32 s2, 0x3e38aa3b
	v_lshl_add_u64 v[120:121], s[6:7], 1, v[144:145]
	v_mov_b32_e32 v141, 0
	v_mul_f32_e32 v118, s2, v118
	v_mul_f32_e32 v119, s2, v119
	v_mul_f32_e32 v116, s2, v116
	v_mul_f32_e32 v117, s2, v117
	v_mul_f32_e32 v114, s2, v114
	v_mul_f32_e32 v115, s2, v115
	v_mul_f32_e32 v112, s2, v112
	v_mul_f32_e32 v113, s2, v113
	v_lshl_add_u64 v[120:121], v[120:121], 0, v[140:141]
	s_mov_b32 s2, 0x4400000
	s_mov_b64 s[6:7], 0x4400000
	v_cvt_pk_bf16_f32 v116, v116, v117
	v_cvt_pk_bf16_f32 v117, v118, v119
	v_add_co_u32_e32 v118, vcc, s2, v120
	v_lshl_add_u64 v[122:123], v[120:121], 0, s[6:7]
	s_nop 0
	v_addc_co_u32_e32 v119, vcc, 0, v121, vcc
	v_cvt_pk_bf16_f32 v112, v112, v113
	v_cvt_pk_bf16_f32 v113, v114, v115
	global_store_dwordx2 v[118:119], v[116:117], off
	global_store_dwordx2 v[122:123], v[112:113], off offset:64

.LBB0_177:
	s_andn2_b64 vcc, exec, s[6:7]
	s_cbranch_vccnz .LBB0_179
	s_waitcnt vmcnt(0)
	v_mul_f32_e32 v132, v106, v117
	v_mul_f32_e32 v134, v106, v116
	v_mov_b32_e32 v106, v111
	v_mov_b32_e32 v126, v113
	v_mov_b32_e32 v127, v115
	v_mul_f32_e32 v130, v110, v116
	v_mul_f32_e32 v144, v110, v117
	v_mul_f32_e32 v152, v106, v118
	v_mul_f32_e32 v153, v107, v119
	v_mov_b32_e32 v110, v107
	v_mov_b32_e32 v122, v112
	v_mov_b32_e32 v123, v114
	v_mul_f32_e32 v128, v104, v126
	v_mul_f32_e32 v129, v105, v127
	v_mov_b32_e32 v131, v152
	v_mov_b32_e32 v133, v153
	v_mul_f32_e32 v106, v110, v118
	v_mul_f32_e32 v107, v111, v119
	v_mul_f32_e32 v104, v104, v122
	v_mul_f32_e32 v105, v105, v123
	v_fma_f32 v122, v108, v122, -v128
	v_fma_f32 v123, v109, v123, -v129
	v_sub_f32_e32 v128, v130, v132
	v_sub_f32_e32 v129, v131, v133
	v_mov_b32_e32 v145, v107
	v_mov_b32_e32 v135, v106
	v_fma_f32 v104, v108, v126, v104
	v_fma_f32 v105, v109, v127, v105
	v_add_f32_e32 v106, v144, v134
	v_add_f32_e32 v107, v145, v135
	v_mov_b32_e32 v108, v122
	v_mov_b32_e32 v109, v123
	v_mov_b32_e32 v110, v128
	v_mov_b32_e32 v111, v129

.LBB0_186:
	s_ashr_i32 s7, s6, 31
	s_mov_b32 s2, 0x3e38aa3b
	v_lshl_add_u64 v[126:127], s[6:7], 1, v[122:123]
	v_mov_b32_e32 v141, 0
	v_mul_f32_e32 v110, s2, v110
	v_mul_f32_e32 v111, s2, v111
	v_mul_f32_e32 v108, s2, v108
	v_mul_f32_e32 v109, s2, v109
	v_mul_f32_e32 v106, s2, v106
	v_mul_f32_e32 v107, s2, v107
	v_mul_f32_e32 v104, s2, v104
	v_mul_f32_e32 v105, s2, v105
	v_lshl_add_u64 v[126:127], v[126:127], 0, v[140:141]
	s_mov_b32 s2, 0x4400000
	s_mov_b64 s[6:7], 0x4400000
	v_cvt_pk_bf16_f32 v108, v108, v109
	v_cvt_pk_bf16_f32 v109, v110, v111
	v_add_co_u32_e32 v110, vcc, s2, v126
	s_waitcnt vmcnt(0)
	v_lshl_add_u64 v[128:129], v[126:127], 0, s[6:7]
	v_addc_co_u32_e32 v111, vcc, 0, v127, vcc
	v_cvt_pk_bf16_f32 v104, v104, v105
	v_cvt_pk_bf16_f32 v105, v106, v107
	global_store_dwordx2 v[110:111], v[108:109], off
	global_store_dwordx2 v[128:129], v[104:105], off offset:64
	v_cndmask_b32_e64 v104, 0, 1, s[8:9]
	v_cmp_ne_u32_e64 s[6:7], 1, v104
	s_andn2_b64 vcc, exec, s[8:9]
	s_cbranch_vccz .LBB0_233

.LBB0_233:
	s_waitcnt vmcnt(0)
	v_mov_b32_e32 v104, v112
	v_mul_f32_e32 v110, v98, v117
	v_mul_f32_e32 v112, v98, v116
	v_mov_b32_e32 v98, v103
	v_mov_b32_e32 v105, v114
	v_mov_b32_e32 v114, v113
	v_mul_f32_e32 v108, v102, v116
	v_mul_f32_e32 v116, v102, v117
	v_mul_f32_e32 v126, v98, v118
	v_mul_f32_e32 v127, v99, v119
	v_mov_b32_e32 v102, v99
	v_mul_f32_e32 v106, v96, v114
	v_mul_f32_e32 v107, v97, v115
	v_mov_b32_e32 v109, v126
	v_mov_b32_e32 v111, v127
	v_mul_f32_e32 v98, v102, v118
	v_mul_f32_e32 v99, v103, v119
	v_mul_f32_e32 v96, v96, v104
	v_mul_f32_e32 v97, v97, v105
	v_fma_f32 v104, v100, v104, -v106
	v_fma_f32 v105, v101, v105, -v107
	v_sub_f32_e32 v106, v108, v110
	v_sub_f32_e32 v107, v109, v111
	v_mov_b32_e32 v117, v99
	v_mov_b32_e32 v113, v98
	v_fma_f32 v96, v100, v114, v96
	v_fma_f32 v97, v101, v115, v97
	v_add_f32_e32 v98, v116, v112
	v_add_f32_e32 v99, v117, v113
	v_mov_b32_e32 v100, v104
	v_mov_b32_e32 v101, v105
	v_mov_b32_e32 v102, v106
	v_mov_b32_e32 v103, v107
	v_cndmask_b32_e64 v104, 0, 1, s[26:27]
	v_cmp_ne_u32_e64 s[8:9], 1, v104
	s_andn2_b64 vcc, exec, s[26:27]
	s_cbranch_vccz .LBB0_188

.LBB0_236:
	s_ashr_i32 s11, s10, 31
	s_mov_b32 s2, 0x3e38aa3b
	v_lshl_add_u64 v[104:105], s[10:11], 1, v[122:123]
	v_mov_b32_e32 v141, 0
	v_mul_f32_e32 v102, s2, v102
	v_mul_f32_e32 v103, s2, v103
	v_mul_f32_e32 v100, s2, v100
	v_mul_f32_e32 v101, s2, v101
	v_mul_f32_e32 v98, s2, v98
	v_mul_f32_e32 v99, s2, v99
	v_mul_f32_e32 v96, s2, v96
	v_mul_f32_e32 v97, s2, v97
	v_lshl_add_u64 v[104:105], v[104:105], 0, v[140:141]
	s_mov_b32 s2, 0x4400000
	s_mov_b64 s[10:11], 0x4400000
	v_cvt_pk_bf16_f32 v100, v100, v101
	v_cvt_pk_bf16_f32 v101, v102, v103
	v_add_co_u32_e32 v102, vcc, s2, v104
	v_lshl_add_u64 v[106:107], v[104:105], 0, s[10:11]
	s_nop 0
	v_addc_co_u32_e32 v103, vcc, 0, v105, vcc
	v_cvt_pk_bf16_f32 v96, v96, v97
	v_cvt_pk_bf16_f32 v97, v98, v99
	global_store_dwordx2 v[102:103], v[100:101], off
	global_store_dwordx2 v[106:107], v[96:97], off offset:64

.LBB0_239:
	s_andn2_b64 vcc, exec, s[26:27]
	s_cbranch_vccnz .LBB0_241
	s_waitcnt vmcnt(0)
	v_mul_f32_e32 v116, v90, v101
	v_mul_f32_e32 v118, v90, v100
	v_mov_b32_e32 v90, v95
	v_mov_b32_e32 v110, v97
	v_mov_b32_e32 v111, v99
	v_mul_f32_e32 v114, v94, v100
	v_mul_f32_e32 v120, v94, v101
	v_mul_f32_e32 v122, v90, v102
	v_mul_f32_e32 v123, v91, v103
	v_mov_b32_e32 v94, v91
	v_mov_b32_e32 v106, v96
	v_mov_b32_e32 v107, v98
	v_mul_f32_e32 v112, v88, v110
	v_mul_f32_e32 v113, v89, v111
	v_mov_b32_e32 v115, v122
	v_mov_b32_e32 v117, v123
	v_mul_f32_e32 v90, v94, v102
	v_mul_f32_e32 v91, v95, v103
	v_mul_f32_e32 v88, v88, v106
	v_mul_f32_e32 v89, v89, v107
	v_fma_f32 v106, v92, v106, -v112
	v_fma_f32 v107, v93, v107, -v113
	v_sub_f32_e32 v112, v114, v116
	v_sub_f32_e32 v113, v115, v117
	v_mov_b32_e32 v121, v91
	v_mov_b32_e32 v119, v90
	v_fma_f32 v88, v92, v110, v88
	v_fma_f32 v89, v93, v111, v89
	v_add_f32_e32 v90, v120, v118
	v_add_f32_e32 v91, v121, v119
	v_mov_b32_e32 v92, v106
	v_mov_b32_e32 v93, v107
	v_mov_b32_e32 v94, v112
	v_mov_b32_e32 v95, v113

.LBB0_248:
	s_ashr_i32 s27, s26, 31
	s_mov_b32 s2, 0x3e38aa3b
	v_lshl_add_u64 v[110:111], s[26:27], 1, v[106:107]
	v_mov_b32_e32 v141, 0
	v_mul_f32_e32 v94, s2, v94
	v_mul_f32_e32 v95, s2, v95
	v_mul_f32_e32 v92, s2, v92
	v_mul_f32_e32 v93, s2, v93
	v_mul_f32_e32 v90, s2, v90
	v_mul_f32_e32 v91, s2, v91
	v_mul_f32_e32 v88, s2, v88
	v_mul_f32_e32 v89, s2, v89
	v_lshl_add_u64 v[110:111], v[110:111], 0, v[140:141]
	s_mov_b32 s2, 0x4400000
	s_mov_b64 s[26:27], 0x4400000
	v_cvt_pk_bf16_f32 v92, v92, v93
	v_cvt_pk_bf16_f32 v93, v94, v95
	v_add_co_u32_e32 v94, vcc, s2, v110
	s_waitcnt vmcnt(0)
	v_lshl_add_u64 v[112:113], v[110:111], 0, s[26:27]
	v_addc_co_u32_e32 v95, vcc, 0, v111, vcc
	v_cvt_pk_bf16_f32 v88, v88, v89
	v_cvt_pk_bf16_f32 v89, v90, v91
	global_store_dwordx2 v[94:95], v[92:93], off
	global_store_dwordx2 v[112:113], v[88:89], off offset:64
	s_and_b64 vcc, exec, s[6:7]
	s_cbranch_vccz .LBB0_295

.LBB0_295:
	s_waitcnt vmcnt(0)
	v_mov_b32_e32 v88, v96
	v_mul_f32_e32 v94, v82, v101
	v_mul_f32_e32 v96, v82, v100
	v_mov_b32_e32 v82, v87
	v_mov_b32_e32 v89, v98
	v_mov_b32_e32 v98, v97
	v_mul_f32_e32 v92, v86, v100
	v_mul_f32_e32 v100, v86, v101
	v_mul_f32_e32 v110, v82, v102
	v_mul_f32_e32 v111, v83, v103
	v_mov_b32_e32 v86, v83
	v_mul_f32_e32 v90, v80, v98
	v_mul_f32_e32 v91, v81, v99
	v_mov_b32_e32 v93, v110
	v_mov_b32_e32 v95, v111
	v_mul_f32_e32 v82, v86, v102
	v_mul_f32_e32 v83, v87, v103
	v_mul_f32_e32 v80, v80, v88
	v_mul_f32_e32 v81, v81, v89
	v_fma_f32 v88, v84, v88, -v90
	v_fma_f32 v89, v85, v89, -v91
	v_sub_f32_e32 v90, v92, v94
	v_sub_f32_e32 v91, v93, v95
	v_mov_b32_e32 v101, v83
	v_mov_b32_e32 v97, v82
	v_fma_f32 v80, v84, v98, v80
	v_fma_f32 v81, v85, v99, v81
	v_add_f32_e32 v82, v100, v96
	v_add_f32_e32 v83, v101, v97
	v_mov_b32_e32 v84, v88
	v_mov_b32_e32 v85, v89
	v_mov_b32_e32 v86, v90
	v_mov_b32_e32 v87, v91
	s_and_b64 vcc, exec, s[8:9]
	s_cbranch_vccz .LBB0_250

.LBB0_298:
	s_ashr_i32 s11, s10, 31
	s_mov_b32 s2, 0x3e38aa3b
	v_lshl_add_u64 v[88:89], s[10:11], 1, v[106:107]
	v_mov_b32_e32 v141, 0
	v_mul_f32_e32 v86, s2, v86
	v_mul_f32_e32 v87, s2, v87
	v_mul_f32_e32 v84, s2, v84
	v_mul_f32_e32 v85, s2, v85
	v_mul_f32_e32 v82, s2, v82
	v_mul_f32_e32 v83, s2, v83
	v_mul_f32_e32 v80, s2, v80
	v_mul_f32_e32 v81, s2, v81
	v_lshl_add_u64 v[88:89], v[88:89], 0, v[140:141]
	s_mov_b32 s2, 0x4400000
	s_mov_b64 s[10:11], 0x4400000
	v_cvt_pk_bf16_f32 v84, v84, v85
	v_cvt_pk_bf16_f32 v85, v86, v87
	v_add_co_u32_e32 v86, vcc, s2, v88
	v_lshl_add_u64 v[90:91], v[88:89], 0, s[10:11]
	s_nop 0
	v_addc_co_u32_e32 v87, vcc, 0, v89, vcc
	v_cvt_pk_bf16_f32 v80, v80, v81
	v_cvt_pk_bf16_f32 v81, v82, v83
	global_store_dwordx2 v[86:87], v[84:85], off
	global_store_dwordx2 v[90:91], v[80:81], off offset:64

.LBB0_301:
	s_andn2_b64 vcc, exec, s[26:27]
	s_cbranch_vccnz .LBB0_303
	s_waitcnt vmcnt(0)
	v_mul_f32_e32 v100, v74, v85
	v_mul_f32_e32 v102, v74, v84
	v_mov_b32_e32 v74, v79
	v_mov_b32_e32 v94, v81
	v_mov_b32_e32 v95, v83
	v_mul_f32_e32 v98, v78, v84
	v_mul_f32_e32 v104, v78, v85
	v_mul_f32_e32 v106, v74, v86
	v_mul_f32_e32 v107, v75, v87
	v_mov_b32_e32 v78, v75
	v_mov_b32_e32 v90, v80
	v_mov_b32_e32 v91, v82
	v_mul_f32_e32 v96, v72, v94
	v_mul_f32_e32 v97, v73, v95
	v_mov_b32_e32 v99, v106
	v_mov_b32_e32 v101, v107
	v_mul_f32_e32 v74, v78, v86
	v_mul_f32_e32 v75, v79, v87
	v_mul_f32_e32 v72, v72, v90
	v_mul_f32_e32 v73, v73, v91
	v_fma_f32 v90, v76, v90, -v96
	v_fma_f32 v91, v77, v91, -v97
	v_sub_f32_e32 v96, v98, v100
	v_sub_f32_e32 v97, v99, v101
	v_mov_b32_e32 v105, v75
	v_mov_b32_e32 v103, v74
	v_fma_f32 v72, v76, v94, v72
	v_fma_f32 v73, v77, v95, v73
	v_add_f32_e32 v74, v104, v102
	v_add_f32_e32 v75, v105, v103
	v_mov_b32_e32 v76, v90
	v_mov_b32_e32 v77, v91
	v_mov_b32_e32 v78, v96
	v_mov_b32_e32 v79, v97

.LBB0_310:
	s_ashr_i32 s27, s26, 31
	s_mov_b32 s2, 0x3e38aa3b
	v_lshl_add_u64 v[94:95], s[26:27], 1, v[90:91]
	v_mov_b32_e32 v141, 0
	v_mul_f32_e32 v78, s2, v78
	v_mul_f32_e32 v79, s2, v79
	v_mul_f32_e32 v76, s2, v76
	v_mul_f32_e32 v77, s2, v77
	v_mul_f32_e32 v74, s2, v74
	v_mul_f32_e32 v75, s2, v75
	v_mul_f32_e32 v72, s2, v72
	v_mul_f32_e32 v73, s2, v73
	v_lshl_add_u64 v[94:95], v[94:95], 0, v[140:141]
	s_mov_b32 s2, 0x4400000
	s_mov_b64 s[26:27], 0x4400000
	v_cvt_pk_bf16_f32 v76, v76, v77
	v_cvt_pk_bf16_f32 v77, v78, v79
	v_add_co_u32_e32 v78, vcc, s2, v94
	s_waitcnt vmcnt(0)
	v_lshl_add_u64 v[96:97], v[94:95], 0, s[26:27]
	v_addc_co_u32_e32 v79, vcc, 0, v95, vcc
	v_cvt_pk_bf16_f32 v72, v72, v73
	v_cvt_pk_bf16_f32 v73, v74, v75
	global_store_dwordx2 v[78:79], v[76:77], off
	global_store_dwordx2 v[96:97], v[72:73], off offset:64
	s_and_b64 vcc, exec, s[6:7]
	s_cbranch_vccz .LBB0_357

.LBB0_357:
	s_waitcnt vmcnt(0)
	v_mov_b32_e32 v72, v80
	v_mul_f32_e32 v78, v66, v85
	v_mul_f32_e32 v80, v66, v84
	v_mov_b32_e32 v66, v71
	v_mov_b32_e32 v73, v82
	v_mov_b32_e32 v82, v81
	v_mul_f32_e32 v76, v70, v84
	v_mul_f32_e32 v84, v70, v85
	v_mul_f32_e32 v94, v66, v86
	v_mul_f32_e32 v95, v67, v87
	v_mov_b32_e32 v70, v67
	v_mul_f32_e32 v74, v64, v82
	v_mul_f32_e32 v75, v65, v83
	v_mov_b32_e32 v77, v94
	v_mov_b32_e32 v79, v95
	v_mul_f32_e32 v66, v70, v86
	v_mul_f32_e32 v67, v71, v87
	v_mul_f32_e32 v64, v64, v72
	v_mul_f32_e32 v65, v65, v73
	v_fma_f32 v72, v68, v72, -v74
	v_fma_f32 v73, v69, v73, -v75
	v_sub_f32_e32 v74, v76, v78
	v_sub_f32_e32 v75, v77, v79
	v_mov_b32_e32 v85, v67
	v_mov_b32_e32 v81, v66
	v_fma_f32 v64, v68, v82, v64
	v_fma_f32 v65, v69, v83, v65
	v_add_f32_e32 v66, v84, v80
	v_add_f32_e32 v67, v85, v81
	v_mov_b32_e32 v68, v72
	v_mov_b32_e32 v69, v73
	v_mov_b32_e32 v70, v74
	v_mov_b32_e32 v71, v75
	s_and_b64 vcc, exec, s[8:9]
	s_cbranch_vccz .LBB0_312

.LBB0_360:
	s_ashr_i32 s11, s10, 31
	s_mov_b32 s2, 0x3e38aa3b
	v_lshl_add_u64 v[72:73], s[10:11], 1, v[90:91]
	v_mov_b32_e32 v141, 0
	v_mul_f32_e32 v70, s2, v70
	v_mul_f32_e32 v71, s2, v71
	v_mul_f32_e32 v68, s2, v68
	v_mul_f32_e32 v69, s2, v69
	v_mul_f32_e32 v66, s2, v66
	v_mul_f32_e32 v67, s2, v67
	v_mul_f32_e32 v64, s2, v64
	v_mul_f32_e32 v65, s2, v65
	v_lshl_add_u64 v[72:73], v[72:73], 0, v[140:141]
	s_mov_b32 s2, 0x4400000
	s_mov_b64 s[10:11], 0x4400000
	v_cvt_pk_bf16_f32 v68, v68, v69
	v_cvt_pk_bf16_f32 v69, v70, v71
	v_add_co_u32_e32 v70, vcc, s2, v72
	v_lshl_add_u64 v[74:75], v[72:73], 0, s[10:11]
	s_nop 0
	v_addc_co_u32_e32 v71, vcc, 0, v73, vcc
	v_cvt_pk_bf16_f32 v64, v64, v65
	v_cvt_pk_bf16_f32 v65, v66, v67
	global_store_dwordx2 v[70:71], v[68:69], off
	global_store_dwordx2 v[74:75], v[64:65], off offset:64

.LBB0_363:
	s_andn2_b64 vcc, exec, s[26:27]
	s_cbranch_vccnz .LBB0_365
	s_waitcnt vmcnt(0)
	v_mul_f32_e32 v84, v58, v69
	v_mul_f32_e32 v86, v58, v68
	v_mov_b32_e32 v58, v63
	v_mov_b32_e32 v78, v65
	v_mov_b32_e32 v79, v67
	v_mul_f32_e32 v82, v62, v68
	v_mul_f32_e32 v88, v62, v69
	v_mul_f32_e32 v90, v58, v70
	v_mul_f32_e32 v91, v59, v71
	v_mov_b32_e32 v62, v59
	v_mov_b32_e32 v74, v64
	v_mov_b32_e32 v75, v66
	v_mul_f32_e32 v80, v56, v78
	v_mul_f32_e32 v81, v57, v79
	v_mov_b32_e32 v83, v90
	v_mov_b32_e32 v85, v91
	v_mul_f32_e32 v58, v62, v70
	v_mul_f32_e32 v59, v63, v71
	v_mul_f32_e32 v56, v56, v74
	v_mul_f32_e32 v57, v57, v75
	v_fma_f32 v74, v60, v74, -v80
	v_fma_f32 v75, v61, v75, -v81
	v_sub_f32_e32 v80, v82, v84
	v_sub_f32_e32 v81, v83, v85
	v_mov_b32_e32 v89, v59
	v_mov_b32_e32 v87, v58
	v_fma_f32 v56, v60, v78, v56
	v_fma_f32 v57, v61, v79, v57
	v_add_f32_e32 v58, v88, v86
	v_add_f32_e32 v59, v89, v87
	v_mov_b32_e32 v60, v74
	v_mov_b32_e32 v61, v75
	v_mov_b32_e32 v62, v80
	v_mov_b32_e32 v63, v81

.LBB0_372:
	s_ashr_i32 s27, s26, 31
	s_mov_b32 s2, 0x3e38aa3b
	v_lshl_add_u64 v[78:79], s[26:27], 1, v[74:75]
	v_mov_b32_e32 v141, 0
	v_mul_f32_e32 v62, s2, v62
	v_mul_f32_e32 v63, s2, v63
	v_mul_f32_e32 v60, s2, v60
	v_mul_f32_e32 v61, s2, v61
	v_mul_f32_e32 v58, s2, v58
	v_mul_f32_e32 v59, s2, v59
	v_mul_f32_e32 v56, s2, v56
	v_mul_f32_e32 v57, s2, v57
	v_lshl_add_u64 v[78:79], v[78:79], 0, v[140:141]
	s_mov_b32 s2, 0x4400000
	s_mov_b64 s[26:27], 0x4400000
	v_cvt_pk_bf16_f32 v60, v60, v61
	v_cvt_pk_bf16_f32 v61, v62, v63
	v_add_co_u32_e32 v62, vcc, s2, v78
	s_waitcnt vmcnt(0)
	v_lshl_add_u64 v[80:81], v[78:79], 0, s[26:27]
	v_addc_co_u32_e32 v63, vcc, 0, v79, vcc
	v_cvt_pk_bf16_f32 v56, v56, v57
	v_cvt_pk_bf16_f32 v57, v58, v59
	global_store_dwordx2 v[62:63], v[60:61], off
	global_store_dwordx2 v[80:81], v[56:57], off offset:64
	s_and_b64 vcc, exec, s[6:7]
	s_cbranch_vccz .LBB0_419

.LBB0_419:
	s_waitcnt vmcnt(0)
	v_mov_b32_e32 v56, v64
	v_mul_f32_e32 v62, v50, v69
	v_mul_f32_e32 v64, v50, v68
	v_mov_b32_e32 v50, v55
	v_mov_b32_e32 v57, v66
	v_mov_b32_e32 v66, v65
	v_mul_f32_e32 v60, v54, v68
	v_mul_f32_e32 v68, v54, v69
	v_mul_f32_e32 v78, v50, v70
	v_mul_f32_e32 v79, v51, v71
	v_mov_b32_e32 v54, v51
	v_mul_f32_e32 v58, v48, v66
	v_mul_f32_e32 v59, v49, v67
	v_mov_b32_e32 v61, v78
	v_mov_b32_e32 v63, v79
	v_mul_f32_e32 v50, v54, v70
	v_mul_f32_e32 v51, v55, v71
	v_mul_f32_e32 v48, v48, v56
	v_mul_f32_e32 v49, v49, v57
	v_fma_f32 v56, v52, v56, -v58
	v_fma_f32 v57, v53, v57, -v59
	v_sub_f32_e32 v58, v60, v62
	v_sub_f32_e32 v59, v61, v63
	v_mov_b32_e32 v69, v51
	v_mov_b32_e32 v65, v50
	v_fma_f32 v48, v52, v66, v48
	v_fma_f32 v49, v53, v67, v49
	v_add_f32_e32 v50, v68, v64
	v_add_f32_e32 v51, v69, v65
	v_mov_b32_e32 v52, v56
	v_mov_b32_e32 v53, v57
	v_mov_b32_e32 v54, v58
	v_mov_b32_e32 v55, v59
	s_and_b64 vcc, exec, s[8:9]
	s_cbranch_vccz .LBB0_374

.LBB0_422:
	s_ashr_i32 s11, s10, 31
	s_mov_b32 s2, 0x3e38aa3b
	v_lshl_add_u64 v[56:57], s[10:11], 1, v[74:75]
	v_mov_b32_e32 v141, 0
	v_mul_f32_e32 v54, s2, v54
	v_mul_f32_e32 v55, s2, v55
	v_mul_f32_e32 v52, s2, v52
	v_mul_f32_e32 v53, s2, v53
	v_mul_f32_e32 v50, s2, v50
	v_mul_f32_e32 v51, s2, v51
	v_mul_f32_e32 v48, s2, v48
	v_mul_f32_e32 v49, s2, v49
	v_lshl_add_u64 v[56:57], v[56:57], 0, v[140:141]
	s_mov_b32 s2, 0x4400000
	s_mov_b64 s[10:11], 0x4400000
	v_cvt_pk_bf16_f32 v52, v52, v53
	v_cvt_pk_bf16_f32 v53, v54, v55
	v_add_co_u32_e32 v54, vcc, s2, v56
	v_lshl_add_u64 v[58:59], v[56:57], 0, s[10:11]
	s_nop 0
	v_addc_co_u32_e32 v55, vcc, 0, v57, vcc
	v_cvt_pk_bf16_f32 v48, v48, v49
	v_cvt_pk_bf16_f32 v49, v50, v51
	global_store_dwordx2 v[54:55], v[52:53], off
	global_store_dwordx2 v[58:59], v[48:49], off offset:64

.LBB0_425:
	s_andn2_b64 vcc, exec, s[26:27]
	s_cbranch_vccnz .LBB0_427
	s_waitcnt vmcnt(0)
	v_mul_f32_e32 v68, v42, v53
	v_mul_f32_e32 v70, v42, v52
	v_mov_b32_e32 v42, v47
	v_mov_b32_e32 v62, v49
	v_mov_b32_e32 v63, v51
	v_mul_f32_e32 v66, v46, v52
	v_mul_f32_e32 v74, v46, v53
	v_mul_f32_e32 v76, v42, v54
	v_mul_f32_e32 v77, v43, v55
	v_mov_b32_e32 v46, v43
	v_mov_b32_e32 v58, v48
	v_mov_b32_e32 v59, v50
	v_mul_f32_e32 v64, v40, v62
	v_mul_f32_e32 v65, v41, v63
	v_mov_b32_e32 v67, v76
	v_mov_b32_e32 v69, v77
	v_mul_f32_e32 v42, v46, v54
	v_mul_f32_e32 v43, v47, v55
	v_mul_f32_e32 v40, v40, v58
	v_mul_f32_e32 v41, v41, v59
	v_fma_f32 v58, v44, v58, -v64
	v_fma_f32 v59, v45, v59, -v65
	v_sub_f32_e32 v64, v66, v68
	v_sub_f32_e32 v65, v67, v69
	v_mov_b32_e32 v75, v43
	v_mov_b32_e32 v71, v42
	v_fma_f32 v40, v44, v62, v40
	v_fma_f32 v41, v45, v63, v41
	v_add_f32_e32 v42, v74, v70
	v_add_f32_e32 v43, v75, v71
	v_mov_b32_e32 v44, v58
	v_mov_b32_e32 v45, v59
	v_mov_b32_e32 v46, v64
	v_mov_b32_e32 v47, v65

.LBB0_434:
	s_ashr_i32 s27, s26, 31
	s_mov_b32 s2, 0x3e38aa3b
	v_lshl_add_u64 v[62:63], s[26:27], 1, v[58:59]
	v_mov_b32_e32 v141, 0
	v_mul_f32_e32 v46, s2, v46
	v_mul_f32_e32 v47, s2, v47
	v_mul_f32_e32 v44, s2, v44
	v_mul_f32_e32 v45, s2, v45
	v_mul_f32_e32 v42, s2, v42
	v_mul_f32_e32 v43, s2, v43
	v_mul_f32_e32 v40, s2, v40
	v_mul_f32_e32 v41, s2, v41
	v_lshl_add_u64 v[62:63], v[62:63], 0, v[140:141]
	s_mov_b32 s2, 0x4400000
	s_mov_b64 s[26:27], 0x4400000
	v_cvt_pk_bf16_f32 v44, v44, v45
	v_cvt_pk_bf16_f32 v45, v46, v47
	v_add_co_u32_e32 v46, vcc, s2, v62
	s_waitcnt vmcnt(0)
	v_lshl_add_u64 v[64:65], v[62:63], 0, s[26:27]
	v_addc_co_u32_e32 v47, vcc, 0, v63, vcc
	v_cvt_pk_bf16_f32 v40, v40, v41
	v_cvt_pk_bf16_f32 v41, v42, v43
	global_store_dwordx2 v[46:47], v[44:45], off
	global_store_dwordx2 v[64:65], v[40:41], off offset:64
	s_and_b64 vcc, exec, s[6:7]
	s_cbranch_vccz .LBB0_481

.LBB0_481:
	s_waitcnt vmcnt(0)
	v_mov_b32_e32 v40, v48
	v_mul_f32_e32 v46, v34, v53
	v_mul_f32_e32 v48, v34, v52
	v_mov_b32_e32 v34, v39
	v_mov_b32_e32 v41, v50
	v_mov_b32_e32 v50, v49
	v_mul_f32_e32 v44, v38, v52
	v_mul_f32_e32 v52, v38, v53
	v_mul_f32_e32 v62, v34, v54
	v_mul_f32_e32 v63, v35, v55
	v_mov_b32_e32 v38, v35
	v_mul_f32_e32 v42, v32, v50
	v_mul_f32_e32 v43, v33, v51
	v_mov_b32_e32 v45, v62
	v_mov_b32_e32 v47, v63
	v_mul_f32_e32 v34, v38, v54
	v_mul_f32_e32 v35, v39, v55
	v_mul_f32_e32 v32, v32, v40
	v_mul_f32_e32 v33, v33, v41
	v_fma_f32 v40, v36, v40, -v42
	v_fma_f32 v41, v37, v41, -v43
	v_sub_f32_e32 v42, v44, v46
	v_sub_f32_e32 v43, v45, v47
	v_mov_b32_e32 v53, v35
	v_mov_b32_e32 v49, v34
	v_fma_f32 v32, v36, v50, v32
	v_fma_f32 v33, v37, v51, v33
	v_add_f32_e32 v34, v52, v48
	v_add_f32_e32 v35, v53, v49
	v_mov_b32_e32 v36, v40
	v_mov_b32_e32 v37, v41
	v_mov_b32_e32 v38, v42
	v_mov_b32_e32 v39, v43
	s_and_b64 vcc, exec, s[8:9]
	s_cbranch_vccz .LBB0_436

.LBB0_484:
	s_ashr_i32 s11, s10, 31
	s_mov_b32 s2, 0x3e38aa3b
	v_lshl_add_u64 v[40:41], s[10:11], 1, v[58:59]
	v_mov_b32_e32 v141, 0
	v_mul_f32_e32 v38, s2, v38
	v_mul_f32_e32 v39, s2, v39
	v_mul_f32_e32 v36, s2, v36
	v_mul_f32_e32 v37, s2, v37
	v_mul_f32_e32 v34, s2, v34
	v_mul_f32_e32 v35, s2, v35
	v_mul_f32_e32 v32, s2, v32
	v_mul_f32_e32 v33, s2, v33
	v_lshl_add_u64 v[40:41], v[40:41], 0, v[140:141]
	s_mov_b32 s2, 0x4400000
	s_mov_b64 s[10:11], 0x4400000
	v_cvt_pk_bf16_f32 v36, v36, v37
	v_cvt_pk_bf16_f32 v37, v38, v39
	v_add_co_u32_e32 v38, vcc, s2, v40
	v_lshl_add_u64 v[42:43], v[40:41], 0, s[10:11]
	s_nop 0
	v_addc_co_u32_e32 v39, vcc, 0, v41, vcc
	v_cvt_pk_bf16_f32 v32, v32, v33
	v_cvt_pk_bf16_f32 v33, v34, v35
	global_store_dwordx2 v[38:39], v[36:37], off
	global_store_dwordx2 v[42:43], v[32:33], off offset:64

.LBB0_487:
	s_andn2_b64 vcc, exec, s[26:27]
	s_cbranch_vccnz .LBB0_489
	s_waitcnt vmcnt(0)
	v_mul_f32_e32 v52, v26, v37
	v_mul_f32_e32 v54, v26, v36
	v_mov_b32_e32 v26, v31
	v_mov_b32_e32 v46, v33
	v_mov_b32_e32 v47, v35
	v_mul_f32_e32 v50, v30, v36
	v_mul_f32_e32 v56, v30, v37
	v_mul_f32_e32 v58, v26, v38
	v_mul_f32_e32 v59, v27, v39
	v_mov_b32_e32 v30, v27
	v_mov_b32_e32 v42, v32
	v_mov_b32_e32 v43, v34
	v_mul_f32_e32 v48, v24, v46
	v_mul_f32_e32 v49, v25, v47
	v_mov_b32_e32 v51, v58
	v_mov_b32_e32 v53, v59
	v_mul_f32_e32 v26, v30, v38
	v_mul_f32_e32 v27, v31, v39
	v_mul_f32_e32 v24, v24, v42
	v_mul_f32_e32 v25, v25, v43
	v_fma_f32 v42, v28, v42, -v48
	v_fma_f32 v43, v29, v43, -v49
	v_sub_f32_e32 v48, v50, v52
	v_sub_f32_e32 v49, v51, v53
	v_mov_b32_e32 v57, v27
	v_mov_b32_e32 v55, v26
	v_fma_f32 v24, v28, v46, v24
	v_fma_f32 v25, v29, v47, v25
	v_add_f32_e32 v26, v56, v54
	v_add_f32_e32 v27, v57, v55
	v_mov_b32_e32 v28, v42
	v_mov_b32_e32 v29, v43
	v_mov_b32_e32 v30, v48
	v_mov_b32_e32 v31, v49

.LBB0_496:
	s_ashr_i32 s27, s26, 31
	s_mov_b32 s2, 0x3e38aa3b
	v_lshl_add_u64 v[46:47], s[26:27], 1, v[42:43]
	v_mov_b32_e32 v141, 0
	v_mul_f32_e32 v30, s2, v30
	v_mul_f32_e32 v31, s2, v31
	v_mul_f32_e32 v28, s2, v28
	v_mul_f32_e32 v29, s2, v29
	v_mul_f32_e32 v26, s2, v26
	v_mul_f32_e32 v27, s2, v27
	v_mul_f32_e32 v24, s2, v24
	v_mul_f32_e32 v25, s2, v25
	v_lshl_add_u64 v[46:47], v[46:47], 0, v[140:141]
	s_mov_b32 s2, 0x4400000
	s_mov_b64 s[26:27], 0x4400000
	v_cvt_pk_bf16_f32 v28, v28, v29
	v_cvt_pk_bf16_f32 v29, v30, v31
	v_add_co_u32_e32 v30, vcc, s2, v46
	s_waitcnt vmcnt(0)
	v_lshl_add_u64 v[48:49], v[46:47], 0, s[26:27]
	v_addc_co_u32_e32 v31, vcc, 0, v47, vcc
	v_cvt_pk_bf16_f32 v24, v24, v25
	v_cvt_pk_bf16_f32 v25, v26, v27
	global_store_dwordx2 v[30:31], v[28:29], off
	global_store_dwordx2 v[48:49], v[24:25], off offset:64
	s_and_b64 vcc, exec, s[6:7]
	s_cbranch_vccz .LBB0_543

.LBB0_543:
	s_waitcnt vmcnt(0)
	v_mov_b32_e32 v24, v32
	v_mul_f32_e32 v30, v18, v37
	v_mul_f32_e32 v32, v18, v36
	v_mov_b32_e32 v18, v23
	v_mov_b32_e32 v25, v34
	v_mov_b32_e32 v34, v33
	v_mul_f32_e32 v28, v22, v36
	v_mul_f32_e32 v36, v22, v37
	v_mul_f32_e32 v46, v18, v38
	v_mul_f32_e32 v47, v19, v39
	v_mov_b32_e32 v22, v19
	v_mul_f32_e32 v26, v16, v34
	v_mul_f32_e32 v27, v17, v35
	v_mov_b32_e32 v29, v46
	v_mov_b32_e32 v31, v47
	v_mul_f32_e32 v18, v22, v38
	v_mul_f32_e32 v19, v23, v39
	v_mul_f32_e32 v16, v16, v24
	v_mul_f32_e32 v17, v17, v25
	v_fma_f32 v24, v20, v24, -v26
	v_fma_f32 v25, v21, v25, -v27
	v_sub_f32_e32 v26, v28, v30
	v_sub_f32_e32 v27, v29, v31
	v_mov_b32_e32 v37, v19
	v_mov_b32_e32 v33, v18
	v_fma_f32 v16, v20, v34, v16
	v_fma_f32 v17, v21, v35, v17
	v_add_f32_e32 v18, v36, v32
	v_add_f32_e32 v19, v37, v33
	v_mov_b32_e32 v20, v24
	v_mov_b32_e32 v21, v25
	v_mov_b32_e32 v22, v26
	v_mov_b32_e32 v23, v27
	s_and_b64 vcc, exec, s[8:9]
	s_cbranch_vccz .LBB0_498

.LBB0_546:
	s_ashr_i32 s11, s10, 31
	s_mov_b32 s2, 0x3e38aa3b
	v_lshl_add_u64 v[24:25], s[10:11], 1, v[42:43]
	v_mov_b32_e32 v141, 0
	v_mul_f32_e32 v22, s2, v22
	v_mul_f32_e32 v23, s2, v23
	v_mul_f32_e32 v20, s2, v20
	v_mul_f32_e32 v21, s2, v21
	v_mul_f32_e32 v18, s2, v18
	v_mul_f32_e32 v19, s2, v19
	v_mul_f32_e32 v16, s2, v16
	v_mul_f32_e32 v17, s2, v17
	v_lshl_add_u64 v[24:25], v[24:25], 0, v[140:141]
	s_mov_b32 s2, 0x4400000
	s_mov_b64 s[10:11], 0x4400000
	v_cvt_pk_bf16_f32 v20, v20, v21
	v_cvt_pk_bf16_f32 v21, v22, v23
	v_add_co_u32_e32 v22, vcc, s2, v24
	v_lshl_add_u64 v[26:27], v[24:25], 0, s[10:11]
	s_nop 0
	v_addc_co_u32_e32 v23, vcc, 0, v25, vcc
	v_cvt_pk_bf16_f32 v16, v16, v17
	v_cvt_pk_bf16_f32 v17, v18, v19
	global_store_dwordx2 v[22:23], v[20:21], off
	global_store_dwordx2 v[26:27], v[16:17], off offset:64

.LBB0_549:
	s_andn2_b64 vcc, exec, s[24:25]
	s_cbranch_vccnz .LBB0_551
	s_waitcnt vmcnt(0)
	v_mul_f32_e32 v36, v10, v21
	v_mul_f32_e32 v38, v10, v20
	v_mov_b32_e32 v10, v15
	v_mov_b32_e32 v30, v17
	v_mov_b32_e32 v31, v19
	v_mul_f32_e32 v34, v14, v20
	v_mul_f32_e32 v40, v14, v21
	v_mul_f32_e32 v42, v10, v22
	v_mul_f32_e32 v43, v11, v23
	v_mov_b32_e32 v14, v11
	v_mov_b32_e32 v26, v16
	v_mov_b32_e32 v27, v18
	v_mul_f32_e32 v32, v8, v30
	v_mul_f32_e32 v33, v9, v31
	v_mov_b32_e32 v35, v42
	v_mov_b32_e32 v37, v43
	v_mul_f32_e32 v10, v14, v22
	v_mul_f32_e32 v11, v15, v23
	v_mul_f32_e32 v8, v8, v26
	v_mul_f32_e32 v9, v9, v27
	v_fma_f32 v26, v12, v26, -v32
	v_fma_f32 v27, v13, v27, -v33
	v_sub_f32_e32 v32, v34, v36
	v_sub_f32_e32 v33, v35, v37
	v_mov_b32_e32 v41, v11
	v_mov_b32_e32 v39, v10
	v_fma_f32 v8, v12, v30, v8
	v_fma_f32 v9, v13, v31, v9
	v_add_f32_e32 v10, v40, v38
	v_add_f32_e32 v11, v41, v39
	v_mov_b32_e32 v12, v26
	v_mov_b32_e32 v13, v27
	v_mov_b32_e32 v14, v32
	v_mov_b32_e32 v15, v33

.LBB0_558:
	s_ashr_i32 s5, s4, 31
	s_mov_b32 s2, 0x3e38aa3b
	v_lshl_add_u64 v[30:31], s[4:5], 1, v[26:27]
	v_mov_b32_e32 v141, 0
	v_mul_f32_e32 v14, s2, v14
	v_mul_f32_e32 v15, s2, v15
	v_mul_f32_e32 v12, s2, v12
	v_mul_f32_e32 v13, s2, v13
	v_mul_f32_e32 v10, s2, v10
	v_mul_f32_e32 v11, s2, v11
	v_mul_f32_e32 v8, s2, v8
	v_mul_f32_e32 v9, s2, v9
	v_lshl_add_u64 v[30:31], v[30:31], 0, v[140:141]
	s_mov_b32 s2, 0x4400000
	s_mov_b64 s[4:5], 0x4400000
	v_cvt_pk_bf16_f32 v12, v12, v13
	v_cvt_pk_bf16_f32 v13, v14, v15
	v_add_co_u32_e32 v14, vcc, s2, v30
	s_waitcnt vmcnt(0)
	v_lshl_add_u64 v[32:33], v[30:31], 0, s[4:5]
	v_addc_co_u32_e32 v15, vcc, 0, v31, vcc
	v_cvt_pk_bf16_f32 v8, v8, v9
	v_cvt_pk_bf16_f32 v9, v10, v11
	global_store_dwordx2 v[14:15], v[12:13], off
	global_store_dwordx2 v[32:33], v[8:9], off offset:64
	s_and_b64 vcc, exec, s[6:7]
	s_cbranch_vccz .LBB0_605

.LBB0_605:
	s_waitcnt vmcnt(0)
	v_mov_b32_e32 v8, v16
	v_mul_f32_e32 v14, v2, v21
	v_mul_f32_e32 v16, v2, v20
	v_mov_b32_e32 v2, v7
	v_mov_b32_e32 v9, v18
	v_mov_b32_e32 v18, v17
	v_mul_f32_e32 v12, v6, v20
	v_mul_f32_e32 v20, v6, v21
	v_mul_f32_e32 v30, v2, v22
	v_mul_f32_e32 v31, v3, v23
	v_mov_b32_e32 v6, v3
	v_mul_f32_e32 v10, v0, v18
	v_mul_f32_e32 v11, v1, v19
	v_mov_b32_e32 v13, v30
	v_mov_b32_e32 v15, v31
	v_mul_f32_e32 v2, v6, v22
	v_mul_f32_e32 v3, v7, v23
	v_mul_f32_e32 v0, v0, v8
	v_mul_f32_e32 v1, v1, v9
	v_fma_f32 v8, v4, v8, -v10
	v_fma_f32 v9, v5, v9, -v11
	v_sub_f32_e32 v10, v12, v14
	v_sub_f32_e32 v11, v13, v15
	v_mov_b32_e32 v21, v3
	v_mov_b32_e32 v17, v2
	v_fma_f32 v0, v4, v18, v0
	v_fma_f32 v1, v5, v19, v1
	v_add_f32_e32 v2, v20, v16
	v_add_f32_e32 v3, v21, v17
	v_mov_b32_e32 v4, v8
	v_mov_b32_e32 v5, v9
	v_mov_b32_e32 v6, v10
	v_mov_b32_e32 v7, v11
	s_and_b64 vcc, exec, s[8:9]
	s_cbranch_vccz .LBB0_560

.LBB0_608:
	s_ashr_i32 s5, s4, 31
	s_mov_b32 s2, 0x3e38aa3b
	v_lshl_add_u64 v[8:9], s[4:5], 1, v[26:27]
	v_mov_b32_e32 v141, 0
	v_mul_f32_e32 v6, s2, v6
	v_mul_f32_e32 v7, s2, v7
	v_mul_f32_e32 v4, s2, v4
	v_mul_f32_e32 v5, s2, v5
	v_mul_f32_e32 v2, s2, v2
	v_mul_f32_e32 v3, s2, v3
	v_mul_f32_e32 v0, s2, v0
	v_mul_f32_e32 v1, s2, v1
	v_lshl_add_u64 v[8:9], v[8:9], 0, v[140:141]
	s_mov_b64 s[2:3], 0x4400000
	v_lshl_add_u64 v[10:11], v[8:9], 0, s[2:3]
	s_mov_b32 s2, 0x4400000
	v_cvt_pk_bf16_f32 v4, v4, v5
	v_cvt_pk_bf16_f32 v5, v6, v7
	v_add_co_u32_e32 v6, vcc, s2, v8
	v_cvt_pk_bf16_f32 v0, v0, v1
	s_nop 0
	v_addc_co_u32_e32 v7, vcc, 0, v9, vcc
	v_cvt_pk_bf16_f32 v1, v2, v3
	global_store_dwordx2 v[6:7], v[4:5], off
	global_store_dwordx2 v[10:11], v[0:1], off offset:64

.LBB0_689:
	s_andn2_b64 vcc, exec, s[6:7]
	s_cbranch_vccnz .LBB0_691
	s_waitcnt vmcnt(0)
	v_mul_f32_e32 v186, v122, v133
	v_mul_f32_e32 v188, v122, v132
	v_mov_b32_e32 v122, v127
	v_mov_b32_e32 v180, v129
	v_mov_b32_e32 v181, v131
	v_mul_f32_e32 v184, v126, v132
	v_mul_f32_e32 v190, v126, v133
	v_mul_f32_e32 v192, v122, v134
	v_mul_f32_e32 v193, v123, v135
	v_mov_b32_e32 v126, v123
	v_mov_b32_e32 v162, v128
	v_mov_b32_e32 v163, v130
	v_mul_f32_e32 v182, v120, v180
	v_mul_f32_e32 v183, v121, v181
	v_mov_b32_e32 v185, v192
	v_mov_b32_e32 v187, v193
	v_mul_f32_e32 v122, v126, v134
	v_mul_f32_e32 v123, v127, v135
	v_mul_f32_e32 v120, v120, v162
	v_mul_f32_e32 v121, v121, v163
	v_fma_f32 v162, v124, v162, -v182
	v_fma_f32 v163, v125, v163, -v183
	v_sub_f32_e32 v182, v184, v186
	v_sub_f32_e32 v183, v185, v187
	v_mov_b32_e32 v191, v123
	v_mov_b32_e32 v189, v122
	v_fma_f32 v120, v124, v180, v120
	v_fma_f32 v121, v125, v181, v121
	v_add_f32_e32 v122, v190, v188
	v_add_f32_e32 v123, v191, v189
	v_mov_b32_e32 v124, v162
	v_mov_b32_e32 v125, v163
	v_mov_b32_e32 v126, v182
	v_mov_b32_e32 v127, v183

.LBB0_711:
	v_lshlrev_b64 v[162:163], 11, v[160:161]
	s_andn2_b64 vcc, exec, s[72:73]
	v_lshl_add_u64 v[162:163], s[56:57], 0, v[162:163]
	s_cbranch_vccnz .LBB0_713
	s_ashr_i32 s11, s10, 31
	v_mul_f32_e32 v126, s60, v126
	v_mul_f32_e32 v127, s60, v127
	v_mul_f32_e32 v124, s60, v124
	v_mul_f32_e32 v125, s60, v125
	v_mul_f32_e32 v122, s60, v122
	v_mul_f32_e32 v123, s60, v123
	v_mul_f32_e32 v120, s60, v120
	v_mul_f32_e32 v121, s60, v121
	v_lshl_add_u64 v[182:183], s[10:11], 1, v[162:163]
	v_lshl_add_u64 v[182:183], v[182:183], 0, v[148:149]
	v_cvt_pk_bf16_f32 v124, v124, v125
	v_cvt_pk_bf16_f32 v125, v126, v127
	v_cvt_pk_bf16_f32 v120, v120, v121
	v_cvt_pk_bf16_f32 v121, v122, v123
	global_store_dwordx2 v[182:183], v[124:125], off
	global_store_dwordx2 v[182:183], v[120:121], off offset:64
.LBB0_713:
	s_add_i32 s2, s24, 0x80000001
	s_cmp_lt_u32 s2, 0x8000000b
	s_cselect_b64 s[10:11], -1, 0
	s_cmp_gt_u32 s2, 0x8000000a
	s_cbranch_scc1 .LBB0_715
	s_waitcnt vmcnt(0)
	v_mov_b32_e32 v120, v128
	v_mul_f32_e32 v126, v114, v133
	v_mul_f32_e32 v128, v114, v132
	v_mov_b32_e32 v114, v119
	v_mov_b32_e32 v121, v130
	v_mov_b32_e32 v130, v129
	v_mul_f32_e32 v124, v118, v132
	v_mul_f32_e32 v132, v118, v133
	v_mul_f32_e32 v182, v114, v134
	v_mul_f32_e32 v183, v115, v135
	v_mov_b32_e32 v118, v115
	v_mul_f32_e32 v122, v112, v130
	v_mul_f32_e32 v123, v113, v131
	v_mov_b32_e32 v125, v182
	v_mov_b32_e32 v127, v183
	v_mul_f32_e32 v114, v118, v134
	v_mul_f32_e32 v115, v119, v135
	v_mul_f32_e32 v112, v112, v120
	v_mul_f32_e32 v113, v113, v121
	v_fma_f32 v120, v116, v120, -v122
	v_fma_f32 v121, v117, v121, -v123
	v_sub_f32_e32 v122, v124, v126
	v_sub_f32_e32 v123, v125, v127
	v_mov_b32_e32 v133, v115
	v_mov_b32_e32 v129, v114
	v_fma_f32 v112, v116, v130, v112
	v_fma_f32 v113, v117, v131, v113
	v_add_f32_e32 v114, v132, v128
	v_add_f32_e32 v115, v133, v129
	v_mov_b32_e32 v116, v120
	v_mov_b32_e32 v117, v121
	v_mov_b32_e32 v118, v122
	v_mov_b32_e32 v119, v123

.LBB0_740:
	s_ashr_i32 s9, s8, 31
	v_mul_f32_e32 v118, s60, v118
	v_mul_f32_e32 v119, s60, v119
	v_mul_f32_e32 v116, s60, v116
	v_mul_f32_e32 v117, s60, v117
	v_mul_f32_e32 v114, s60, v114
	v_mul_f32_e32 v115, s60, v115
	v_mul_f32_e32 v112, s60, v112
	v_mul_f32_e32 v113, s60, v113
	v_lshl_add_u64 v[120:121], s[8:9], 1, v[162:163]
	v_lshl_add_u64 v[120:121], v[120:121], 0, v[148:149]
	v_cvt_pk_bf16_f32 v116, v116, v117
	v_cvt_pk_bf16_f32 v117, v118, v119
	v_cvt_pk_bf16_f32 v112, v112, v113
	v_cvt_pk_bf16_f32 v113, v114, v115
	global_store_dwordx2 v[120:121], v[116:117], off
	global_store_dwordx2 v[120:121], v[112:113], off offset:64

.LBB0_743:
	s_andn2_b64 vcc, exec, s[8:9]
	s_cbranch_vccnz .LBB0_745
	s_waitcnt vmcnt(0)
	v_mul_f32_e32 v132, v106, v117
	v_mul_f32_e32 v134, v106, v116
	v_mov_b32_e32 v106, v111
	v_mov_b32_e32 v126, v113
	v_mov_b32_e32 v127, v115
	v_mul_f32_e32 v130, v110, v116
	v_mul_f32_e32 v162, v110, v117
	v_mul_f32_e32 v180, v106, v118
	v_mul_f32_e32 v181, v107, v119
	v_mov_b32_e32 v110, v107
	v_mov_b32_e32 v122, v112
	v_mov_b32_e32 v123, v114
	v_mul_f32_e32 v128, v104, v126
	v_mul_f32_e32 v129, v105, v127
	v_mov_b32_e32 v131, v180
	v_mov_b32_e32 v133, v181
	v_mul_f32_e32 v106, v110, v118
	v_mul_f32_e32 v107, v111, v119
	v_mul_f32_e32 v104, v104, v122
	v_mul_f32_e32 v105, v105, v123
	v_fma_f32 v122, v108, v122, -v128
	v_fma_f32 v123, v109, v123, -v129
	v_sub_f32_e32 v128, v130, v132
	v_sub_f32_e32 v129, v131, v133
	v_mov_b32_e32 v163, v107
	v_mov_b32_e32 v135, v106
	v_fma_f32 v104, v108, v126, v104
	v_fma_f32 v105, v109, v127, v105
	v_add_f32_e32 v106, v162, v134
	v_add_f32_e32 v107, v163, v135
	v_mov_b32_e32 v108, v122
	v_mov_b32_e32 v109, v123
	v_mov_b32_e32 v110, v128
	v_mov_b32_e32 v111, v129

.LBB0_765:
	s_waitcnt vmcnt(0)
	v_mov_b32_e32 v104, v112
	v_mul_f32_e32 v110, v98, v117
	v_mul_f32_e32 v112, v98, v116
	v_mov_b32_e32 v98, v103
	v_mov_b32_e32 v105, v114
	v_mov_b32_e32 v114, v113
	v_mul_f32_e32 v108, v102, v116
	v_mul_f32_e32 v116, v102, v117
	v_mul_f32_e32 v126, v98, v118
	v_mul_f32_e32 v127, v99, v119
	v_mov_b32_e32 v102, v99
	v_mul_f32_e32 v106, v96, v114
	v_mul_f32_e32 v107, v97, v115
	v_mov_b32_e32 v109, v126
	v_mov_b32_e32 v111, v127
	v_mul_f32_e32 v98, v102, v118
	v_mul_f32_e32 v99, v103, v119
	v_mul_f32_e32 v96, v96, v104
	v_mul_f32_e32 v97, v97, v105
	v_fma_f32 v104, v100, v104, -v106
	v_fma_f32 v105, v101, v105, -v107
	v_sub_f32_e32 v106, v108, v110
	v_sub_f32_e32 v107, v109, v111
	v_mov_b32_e32 v117, v99
	v_mov_b32_e32 v113, v98
	v_fma_f32 v96, v100, v114, v96
	v_fma_f32 v97, v101, v115, v97
	v_add_f32_e32 v98, v116, v112
	v_add_f32_e32 v99, v117, v113
	v_mov_b32_e32 v100, v104
	v_mov_b32_e32 v101, v105
	v_mov_b32_e32 v102, v106
	v_mov_b32_e32 v103, v107
	v_cndmask_b32_e64 v104, 0, 1, s[72:73]
	v_cmp_ne_u32_e64 s[10:11], 1, v104
	s_andn2_b64 vcc, exec, s[72:73]
	s_cbranch_vccz .LBB0_969

.LBB0_768:
	s_ashr_i32 s13, s12, 31
	v_mul_f32_e32 v102, s60, v102
	v_mul_f32_e32 v103, s60, v103
	v_mul_f32_e32 v100, s60, v100
	v_mul_f32_e32 v101, s60, v101
	v_mul_f32_e32 v98, s60, v98
	v_mul_f32_e32 v99, s60, v99
	v_mul_f32_e32 v96, s60, v96
	v_mul_f32_e32 v97, s60, v97
	v_lshl_add_u64 v[104:105], s[12:13], 1, v[122:123]
	v_lshl_add_u64 v[104:105], v[104:105], 0, v[148:149]
	v_cvt_pk_bf16_f32 v100, v100, v101
	v_cvt_pk_bf16_f32 v101, v102, v103
	v_cvt_pk_bf16_f32 v96, v96, v97
	v_cvt_pk_bf16_f32 v97, v98, v99
	global_store_dwordx2 v[104:105], v[100:101], off
	global_store_dwordx2 v[104:105], v[96:97], off offset:64

.LBB0_771:
	s_andn2_b64 vcc, exec, s[72:73]
	s_cbranch_vccnz .LBB0_773
	s_waitcnt vmcnt(0)
	v_mul_f32_e32 v116, v90, v101
	v_mul_f32_e32 v118, v90, v100
	v_mov_b32_e32 v90, v95
	v_mov_b32_e32 v110, v97
	v_mov_b32_e32 v111, v99
	v_mul_f32_e32 v114, v94, v100
	v_mul_f32_e32 v120, v94, v101
	v_mul_f32_e32 v122, v90, v102
	v_mul_f32_e32 v123, v91, v103
	v_mov_b32_e32 v94, v91
	v_mov_b32_e32 v106, v96
	v_mov_b32_e32 v107, v98
	v_mul_f32_e32 v112, v88, v110
	v_mul_f32_e32 v113, v89, v111
	v_mov_b32_e32 v115, v122
	v_mov_b32_e32 v117, v123
	v_mul_f32_e32 v90, v94, v102
	v_mul_f32_e32 v91, v95, v103
	v_mul_f32_e32 v88, v88, v106
	v_mul_f32_e32 v89, v89, v107
	v_fma_f32 v106, v92, v106, -v112
	v_fma_f32 v107, v93, v107, -v113
	v_sub_f32_e32 v112, v114, v116
	v_sub_f32_e32 v113, v115, v117
	v_mov_b32_e32 v121, v91
	v_mov_b32_e32 v119, v90
	v_fma_f32 v88, v92, v110, v88
	v_fma_f32 v89, v93, v111, v89
	v_add_f32_e32 v90, v120, v118
	v_add_f32_e32 v91, v121, v119
	v_mov_b32_e32 v92, v106
	v_mov_b32_e32 v93, v107
	v_mov_b32_e32 v94, v112
	v_mov_b32_e32 v95, v113

.LBB0_793:
	s_waitcnt vmcnt(0)
	v_mov_b32_e32 v88, v96
	v_mul_f32_e32 v94, v82, v101
	v_mul_f32_e32 v96, v82, v100
	v_mov_b32_e32 v82, v87
	v_mov_b32_e32 v89, v98
	v_mov_b32_e32 v98, v97
	v_mul_f32_e32 v92, v86, v100
	v_mul_f32_e32 v100, v86, v101
	v_mul_f32_e32 v110, v82, v102
	v_mul_f32_e32 v111, v83, v103
	v_mov_b32_e32 v86, v83
	v_mul_f32_e32 v90, v80, v98
	v_mul_f32_e32 v91, v81, v99
	v_mov_b32_e32 v93, v110
	v_mov_b32_e32 v95, v111
	v_mul_f32_e32 v82, v86, v102
	v_mul_f32_e32 v83, v87, v103
	v_mul_f32_e32 v80, v80, v88
	v_mul_f32_e32 v81, v81, v89
	v_fma_f32 v88, v84, v88, -v90
	v_fma_f32 v89, v85, v89, -v91
	v_sub_f32_e32 v90, v92, v94
	v_sub_f32_e32 v91, v93, v95
	v_mov_b32_e32 v101, v83
	v_mov_b32_e32 v97, v82
	v_fma_f32 v80, v84, v98, v80
	v_fma_f32 v81, v85, v99, v81
	v_add_f32_e32 v82, v100, v96
	v_add_f32_e32 v83, v101, v97
	v_mov_b32_e32 v84, v88
	v_mov_b32_e32 v85, v89
	v_mov_b32_e32 v86, v90
	v_mov_b32_e32 v87, v91
	s_and_b64 vcc, exec, s[10:11]
	s_cbranch_vccz .LBB0_995

.LBB0_796:
	s_ashr_i32 s13, s12, 31
	v_mul_f32_e32 v86, s60, v86
	v_mul_f32_e32 v87, s60, v87
	v_mul_f32_e32 v84, s60, v84
	v_mul_f32_e32 v85, s60, v85
	v_mul_f32_e32 v82, s60, v82
	v_mul_f32_e32 v83, s60, v83
	v_mul_f32_e32 v80, s60, v80
	v_mul_f32_e32 v81, s60, v81
	v_lshl_add_u64 v[88:89], s[12:13], 1, v[106:107]
	v_lshl_add_u64 v[88:89], v[88:89], 0, v[148:149]
	v_cvt_pk_bf16_f32 v84, v84, v85
	v_cvt_pk_bf16_f32 v85, v86, v87
	v_cvt_pk_bf16_f32 v80, v80, v81
	v_cvt_pk_bf16_f32 v81, v82, v83
	global_store_dwordx2 v[88:89], v[84:85], off
	global_store_dwordx2 v[88:89], v[80:81], off offset:64

.LBB0_799:
	s_andn2_b64 vcc, exec, s[72:73]
	s_cbranch_vccnz .LBB0_801
	s_waitcnt vmcnt(0)
	v_mul_f32_e32 v100, v74, v85
	v_mul_f32_e32 v102, v74, v84
	v_mov_b32_e32 v74, v79
	v_mov_b32_e32 v94, v81
	v_mov_b32_e32 v95, v83
	v_mul_f32_e32 v98, v78, v84
	v_mul_f32_e32 v104, v78, v85
	v_mul_f32_e32 v106, v74, v86
	v_mul_f32_e32 v107, v75, v87
	v_mov_b32_e32 v78, v75
	v_mov_b32_e32 v90, v80
	v_mov_b32_e32 v91, v82
	v_mul_f32_e32 v96, v72, v94
	v_mul_f32_e32 v97, v73, v95
	v_mov_b32_e32 v99, v106
	v_mov_b32_e32 v101, v107
	v_mul_f32_e32 v74, v78, v86
	v_mul_f32_e32 v75, v79, v87
	v_mul_f32_e32 v72, v72, v90
	v_mul_f32_e32 v73, v73, v91
	v_fma_f32 v90, v76, v90, -v96
	v_fma_f32 v91, v77, v91, -v97
	v_sub_f32_e32 v96, v98, v100
	v_sub_f32_e32 v97, v99, v101
	v_mov_b32_e32 v105, v75
	v_mov_b32_e32 v103, v74
	v_fma_f32 v72, v76, v94, v72
	v_fma_f32 v73, v77, v95, v73
	v_add_f32_e32 v74, v104, v102
	v_add_f32_e32 v75, v105, v103
	v_mov_b32_e32 v76, v90
	v_mov_b32_e32 v77, v91
	v_mov_b32_e32 v78, v96
	v_mov_b32_e32 v79, v97

.LBB0_821:
	s_waitcnt vmcnt(0)
	v_mov_b32_e32 v72, v80
	v_mul_f32_e32 v78, v66, v85
	v_mul_f32_e32 v80, v66, v84
	v_mov_b32_e32 v66, v71
	v_mov_b32_e32 v73, v82
	v_mov_b32_e32 v82, v81
	v_mul_f32_e32 v76, v70, v84
	v_mul_f32_e32 v84, v70, v85
	v_mul_f32_e32 v94, v66, v86
	v_mul_f32_e32 v95, v67, v87
	v_mov_b32_e32 v70, v67
	v_mul_f32_e32 v74, v64, v82
	v_mul_f32_e32 v75, v65, v83
	v_mov_b32_e32 v77, v94
	v_mov_b32_e32 v79, v95
	v_mul_f32_e32 v66, v70, v86
	v_mul_f32_e32 v67, v71, v87
	v_mul_f32_e32 v64, v64, v72
	v_mul_f32_e32 v65, v65, v73
	v_fma_f32 v72, v68, v72, -v74
	v_fma_f32 v73, v69, v73, -v75
	v_sub_f32_e32 v74, v76, v78
	v_sub_f32_e32 v75, v77, v79
	v_mov_b32_e32 v85, v67
	v_mov_b32_e32 v81, v66
	v_fma_f32 v64, v68, v82, v64
	v_fma_f32 v65, v69, v83, v65
	v_add_f32_e32 v66, v84, v80
	v_add_f32_e32 v67, v85, v81
	v_mov_b32_e32 v68, v72
	v_mov_b32_e32 v69, v73
	v_mov_b32_e32 v70, v74
	v_mov_b32_e32 v71, v75
	s_and_b64 vcc, exec, s[10:11]
	s_cbranch_vccz .LBB0_1021

.LBB0_824:
	s_ashr_i32 s13, s12, 31
	v_mul_f32_e32 v70, s60, v70
	v_mul_f32_e32 v71, s60, v71
	v_mul_f32_e32 v68, s60, v68
	v_mul_f32_e32 v69, s60, v69
	v_mul_f32_e32 v66, s60, v66
	v_mul_f32_e32 v67, s60, v67
	v_mul_f32_e32 v64, s60, v64
	v_mul_f32_e32 v65, s60, v65
	v_lshl_add_u64 v[72:73], s[12:13], 1, v[90:91]
	v_lshl_add_u64 v[72:73], v[72:73], 0, v[148:149]
	v_cvt_pk_bf16_f32 v68, v68, v69
	v_cvt_pk_bf16_f32 v69, v70, v71
	v_cvt_pk_bf16_f32 v64, v64, v65
	v_cvt_pk_bf16_f32 v65, v66, v67
	global_store_dwordx2 v[72:73], v[68:69], off
	global_store_dwordx2 v[72:73], v[64:65], off offset:64

.LBB0_827:
	s_andn2_b64 vcc, exec, s[72:73]
	s_cbranch_vccnz .LBB0_829
	s_waitcnt vmcnt(0)
	v_mul_f32_e32 v84, v58, v69
	v_mul_f32_e32 v86, v58, v68
	v_mov_b32_e32 v58, v63
	v_mov_b32_e32 v78, v65
	v_mov_b32_e32 v79, v67
	v_mul_f32_e32 v82, v62, v68
	v_mul_f32_e32 v88, v62, v69
	v_mul_f32_e32 v90, v58, v70
	v_mul_f32_e32 v91, v59, v71
	v_mov_b32_e32 v62, v59
	v_mov_b32_e32 v74, v64
	v_mov_b32_e32 v75, v66
	v_mul_f32_e32 v80, v56, v78
	v_mul_f32_e32 v81, v57, v79
	v_mov_b32_e32 v83, v90
	v_mov_b32_e32 v85, v91
	v_mul_f32_e32 v58, v62, v70
	v_mul_f32_e32 v59, v63, v71
	v_mul_f32_e32 v56, v56, v74
	v_mul_f32_e32 v57, v57, v75
	v_fma_f32 v74, v60, v74, -v80
	v_fma_f32 v75, v61, v75, -v81
	v_sub_f32_e32 v80, v82, v84
	v_sub_f32_e32 v81, v83, v85
	v_mov_b32_e32 v89, v59
	v_mov_b32_e32 v87, v58
	v_fma_f32 v56, v60, v78, v56
	v_fma_f32 v57, v61, v79, v57
	v_add_f32_e32 v58, v88, v86
	v_add_f32_e32 v59, v89, v87
	v_mov_b32_e32 v60, v74
	v_mov_b32_e32 v61, v75
	v_mov_b32_e32 v62, v80
	v_mov_b32_e32 v63, v81

.LBB0_849:
	s_waitcnt vmcnt(0)
	v_mov_b32_e32 v56, v64
	v_mul_f32_e32 v62, v50, v69
	v_mul_f32_e32 v64, v50, v68
	v_mov_b32_e32 v50, v55
	v_mov_b32_e32 v57, v66
	v_mov_b32_e32 v66, v65
	v_mul_f32_e32 v60, v54, v68
	v_mul_f32_e32 v68, v54, v69
	v_mul_f32_e32 v78, v50, v70
	v_mul_f32_e32 v79, v51, v71
	v_mov_b32_e32 v54, v51
	v_mul_f32_e32 v58, v48, v66
	v_mul_f32_e32 v59, v49, v67
	v_mov_b32_e32 v61, v78
	v_mov_b32_e32 v63, v79
	v_mul_f32_e32 v50, v54, v70
	v_mul_f32_e32 v51, v55, v71
	v_mul_f32_e32 v48, v48, v56
	v_mul_f32_e32 v49, v49, v57
	v_fma_f32 v56, v52, v56, -v58
	v_fma_f32 v57, v53, v57, -v59
	v_sub_f32_e32 v58, v60, v62
	v_sub_f32_e32 v59, v61, v63
	v_mov_b32_e32 v69, v51
	v_mov_b32_e32 v65, v50
	v_fma_f32 v48, v52, v66, v48
	v_fma_f32 v49, v53, v67, v49
	v_add_f32_e32 v50, v68, v64
	v_add_f32_e32 v51, v69, v65
	v_mov_b32_e32 v52, v56
	v_mov_b32_e32 v53, v57
	v_mov_b32_e32 v54, v58
	v_mov_b32_e32 v55, v59
	s_and_b64 vcc, exec, s[10:11]
	s_cbranch_vccz .LBB0_1047

.LBB0_852:
	s_ashr_i32 s13, s12, 31
	v_mul_f32_e32 v54, s60, v54
	v_mul_f32_e32 v55, s60, v55
	v_mul_f32_e32 v52, s60, v52
	v_mul_f32_e32 v53, s60, v53
	v_mul_f32_e32 v50, s60, v50
	v_mul_f32_e32 v51, s60, v51
	v_mul_f32_e32 v48, s60, v48
	v_mul_f32_e32 v49, s60, v49
	v_lshl_add_u64 v[56:57], s[12:13], 1, v[74:75]
	v_lshl_add_u64 v[56:57], v[56:57], 0, v[148:149]
	v_cvt_pk_bf16_f32 v52, v52, v53
	v_cvt_pk_bf16_f32 v53, v54, v55
	v_cvt_pk_bf16_f32 v48, v48, v49
	v_cvt_pk_bf16_f32 v49, v50, v51
	global_store_dwordx2 v[56:57], v[52:53], off
	global_store_dwordx2 v[56:57], v[48:49], off offset:64

.LBB0_855:
	s_andn2_b64 vcc, exec, s[72:73]
	s_cbranch_vccnz .LBB0_857
	s_waitcnt vmcnt(0)
	v_mul_f32_e32 v68, v42, v53
	v_mul_f32_e32 v70, v42, v52
	v_mov_b32_e32 v42, v47
	v_mov_b32_e32 v62, v49
	v_mov_b32_e32 v63, v51
	v_mul_f32_e32 v66, v46, v52
	v_mul_f32_e32 v74, v46, v53
	v_mul_f32_e32 v76, v42, v54
	v_mul_f32_e32 v77, v43, v55
	v_mov_b32_e32 v46, v43
	v_mov_b32_e32 v58, v48
	v_mov_b32_e32 v59, v50
	v_mul_f32_e32 v64, v40, v62
	v_mul_f32_e32 v65, v41, v63
	v_mov_b32_e32 v67, v76
	v_mov_b32_e32 v69, v77
	v_mul_f32_e32 v42, v46, v54
	v_mul_f32_e32 v43, v47, v55
	v_mul_f32_e32 v40, v40, v58
	v_mul_f32_e32 v41, v41, v59
	v_fma_f32 v58, v44, v58, -v64
	v_fma_f32 v59, v45, v59, -v65
	v_sub_f32_e32 v64, v66, v68
	v_sub_f32_e32 v65, v67, v69
	v_mov_b32_e32 v75, v43
	v_mov_b32_e32 v71, v42
	v_fma_f32 v40, v44, v62, v40
	v_fma_f32 v41, v45, v63, v41
	v_add_f32_e32 v42, v74, v70
	v_add_f32_e32 v43, v75, v71
	v_mov_b32_e32 v44, v58
	v_mov_b32_e32 v45, v59
	v_mov_b32_e32 v46, v64
	v_mov_b32_e32 v47, v65

.LBB0_877:
	s_waitcnt vmcnt(0)
	v_mov_b32_e32 v40, v48
	v_mul_f32_e32 v46, v34, v53
	v_mul_f32_e32 v48, v34, v52
	v_mov_b32_e32 v34, v39
	v_mov_b32_e32 v41, v50
	v_mov_b32_e32 v50, v49
	v_mul_f32_e32 v44, v38, v52
	v_mul_f32_e32 v52, v38, v53
	v_mul_f32_e32 v62, v34, v54
	v_mul_f32_e32 v63, v35, v55
	v_mov_b32_e32 v38, v35
	v_mul_f32_e32 v42, v32, v50
	v_mul_f32_e32 v43, v33, v51
	v_mov_b32_e32 v45, v62
	v_mov_b32_e32 v47, v63
	v_mul_f32_e32 v34, v38, v54
	v_mul_f32_e32 v35, v39, v55
	v_mul_f32_e32 v32, v32, v40
	v_mul_f32_e32 v33, v33, v41
	v_fma_f32 v40, v36, v40, -v42
	v_fma_f32 v41, v37, v41, -v43
	v_sub_f32_e32 v42, v44, v46
	v_sub_f32_e32 v43, v45, v47
	v_mov_b32_e32 v53, v35
	v_mov_b32_e32 v49, v34
	v_fma_f32 v32, v36, v50, v32
	v_fma_f32 v33, v37, v51, v33
	v_add_f32_e32 v34, v52, v48
	v_add_f32_e32 v35, v53, v49
	v_mov_b32_e32 v36, v40
	v_mov_b32_e32 v37, v41
	v_mov_b32_e32 v38, v42
	v_mov_b32_e32 v39, v43
	s_and_b64 vcc, exec, s[10:11]
	s_cbranch_vccz .LBB0_1073

.LBB0_880:
	s_ashr_i32 s13, s12, 31
	v_mul_f32_e32 v38, s60, v38
	v_mul_f32_e32 v39, s60, v39
	v_mul_f32_e32 v36, s60, v36
	v_mul_f32_e32 v37, s60, v37
	v_mul_f32_e32 v34, s60, v34
	v_mul_f32_e32 v35, s60, v35
	v_mul_f32_e32 v32, s60, v32
	v_mul_f32_e32 v33, s60, v33
	v_lshl_add_u64 v[40:41], s[12:13], 1, v[58:59]
	v_lshl_add_u64 v[40:41], v[40:41], 0, v[148:149]
	v_cvt_pk_bf16_f32 v36, v36, v37
	v_cvt_pk_bf16_f32 v37, v38, v39
	v_cvt_pk_bf16_f32 v32, v32, v33
	v_cvt_pk_bf16_f32 v33, v34, v35
	global_store_dwordx2 v[40:41], v[36:37], off
	global_store_dwordx2 v[40:41], v[32:33], off offset:64

.LBB0_883:
	s_andn2_b64 vcc, exec, s[72:73]
	s_cbranch_vccnz .LBB0_885
	s_waitcnt vmcnt(0)
	v_mul_f32_e32 v52, v26, v37
	v_mul_f32_e32 v54, v26, v36
	v_mov_b32_e32 v26, v31
	v_mov_b32_e32 v46, v33
	v_mov_b32_e32 v47, v35
	v_mul_f32_e32 v50, v30, v36
	v_mul_f32_e32 v56, v30, v37
	v_mul_f32_e32 v58, v26, v38
	v_mul_f32_e32 v59, v27, v39
	v_mov_b32_e32 v30, v27
	v_mov_b32_e32 v42, v32
	v_mov_b32_e32 v43, v34
	v_mul_f32_e32 v48, v24, v46
	v_mul_f32_e32 v49, v25, v47
	v_mov_b32_e32 v51, v58
	v_mov_b32_e32 v53, v59
	v_mul_f32_e32 v26, v30, v38
	v_mul_f32_e32 v27, v31, v39
	v_mul_f32_e32 v24, v24, v42
	v_mul_f32_e32 v25, v25, v43
	v_fma_f32 v42, v28, v42, -v48
	v_fma_f32 v43, v29, v43, -v49
	v_sub_f32_e32 v48, v50, v52
	v_sub_f32_e32 v49, v51, v53
	v_mov_b32_e32 v57, v27
	v_mov_b32_e32 v55, v26
	v_fma_f32 v24, v28, v46, v24
	v_fma_f32 v25, v29, v47, v25
	v_add_f32_e32 v26, v56, v54
	v_add_f32_e32 v27, v57, v55
	v_mov_b32_e32 v28, v42
	v_mov_b32_e32 v29, v43
	v_mov_b32_e32 v30, v48
	v_mov_b32_e32 v31, v49

.LBB0_905:
	s_waitcnt vmcnt(0)
	v_mov_b32_e32 v24, v32
	v_mul_f32_e32 v30, v18, v37
	v_mul_f32_e32 v32, v18, v36
	v_mov_b32_e32 v18, v23
	v_mov_b32_e32 v25, v34
	v_mov_b32_e32 v34, v33
	v_mul_f32_e32 v28, v22, v36
	v_mul_f32_e32 v36, v22, v37
	v_mul_f32_e32 v46, v18, v38
	v_mul_f32_e32 v47, v19, v39
	v_mov_b32_e32 v22, v19
	v_mul_f32_e32 v26, v16, v34
	v_mul_f32_e32 v27, v17, v35
	v_mov_b32_e32 v29, v46
	v_mov_b32_e32 v31, v47
	v_mul_f32_e32 v18, v22, v38
	v_mul_f32_e32 v19, v23, v39
	v_mul_f32_e32 v16, v16, v24
	v_mul_f32_e32 v17, v17, v25
	v_fma_f32 v24, v20, v24, -v26
	v_fma_f32 v25, v21, v25, -v27
	v_sub_f32_e32 v26, v28, v30
	v_sub_f32_e32 v27, v29, v31
	v_mov_b32_e32 v37, v19
	v_mov_b32_e32 v33, v18
	v_fma_f32 v16, v20, v34, v16
	v_fma_f32 v17, v21, v35, v17
	v_add_f32_e32 v18, v36, v32
	v_add_f32_e32 v19, v37, v33
	v_mov_b32_e32 v20, v24
	v_mov_b32_e32 v21, v25
	v_mov_b32_e32 v22, v26
	v_mov_b32_e32 v23, v27
	s_and_b64 vcc, exec, s[10:11]
	s_cbranch_vccz .LBB0_1099

.LBB0_908:
	s_ashr_i32 s13, s12, 31
	v_mul_f32_e32 v22, s60, v22
	v_mul_f32_e32 v23, s60, v23
	v_mul_f32_e32 v20, s60, v20
	v_mul_f32_e32 v21, s60, v21
	v_mul_f32_e32 v18, s60, v18
	v_mul_f32_e32 v19, s60, v19
	v_mul_f32_e32 v16, s60, v16
	v_mul_f32_e32 v17, s60, v17
	v_lshl_add_u64 v[24:25], s[12:13], 1, v[42:43]
	v_lshl_add_u64 v[24:25], v[24:25], 0, v[148:149]
	v_cvt_pk_bf16_f32 v20, v20, v21
	v_cvt_pk_bf16_f32 v21, v22, v23
	v_cvt_pk_bf16_f32 v16, v16, v17
	v_cvt_pk_bf16_f32 v17, v18, v19
	global_store_dwordx2 v[24:25], v[20:21], off
	global_store_dwordx2 v[24:25], v[16:17], off offset:64

.LBB0_911:
	s_andn2_b64 vcc, exec, s[70:71]
	s_cbranch_vccnz .LBB0_913
	s_waitcnt vmcnt(0)
	v_mul_f32_e32 v36, v10, v21
	v_mul_f32_e32 v38, v10, v20
	v_mov_b32_e32 v10, v15
	v_mov_b32_e32 v30, v17
	v_mov_b32_e32 v31, v19
	v_mul_f32_e32 v34, v14, v20
	v_mul_f32_e32 v40, v14, v21
	v_mul_f32_e32 v42, v10, v22
	v_mul_f32_e32 v43, v11, v23
	v_mov_b32_e32 v14, v11
	v_mov_b32_e32 v26, v16
	v_mov_b32_e32 v27, v18
	v_mul_f32_e32 v32, v8, v30
	v_mul_f32_e32 v33, v9, v31
	v_mov_b32_e32 v35, v42
	v_mov_b32_e32 v37, v43
	v_mul_f32_e32 v10, v14, v22
	v_mul_f32_e32 v11, v15, v23
	v_mul_f32_e32 v8, v8, v26
	v_mul_f32_e32 v9, v9, v27
	v_fma_f32 v26, v12, v26, -v32
	v_fma_f32 v27, v13, v27, -v33
	v_sub_f32_e32 v32, v34, v36
	v_sub_f32_e32 v33, v35, v37
	v_mov_b32_e32 v41, v11
	v_mov_b32_e32 v39, v10
	v_fma_f32 v8, v12, v30, v8
	v_fma_f32 v9, v13, v31, v9
	v_add_f32_e32 v10, v40, v38
	v_add_f32_e32 v11, v41, v39
	v_mov_b32_e32 v12, v26
	v_mov_b32_e32 v13, v27
	v_mov_b32_e32 v14, v32
	v_mov_b32_e32 v15, v33

.LBB0_932:
	v_lshlrev_b64 v[26:27], 11, v[24:25]
	s_andn2_b64 vcc, exec, s[72:73]
	v_lshl_add_u64 v[26:27], s[56:57], 0, v[26:27]
	v_readlane_b32 s70, v240, 6
	s_cbranch_vccnz .LBB0_955
	s_ashr_i32 s7, s6, 31
	v_mul_f32_e32 v14, s60, v14
	v_mul_f32_e32 v15, s60, v15
	v_mul_f32_e32 v12, s60, v12
	v_mul_f32_e32 v13, s60, v13
	v_mul_f32_e32 v10, s60, v10
	v_mul_f32_e32 v11, s60, v11
	v_mul_f32_e32 v8, s60, v8
	v_mul_f32_e32 v9, s60, v9
	v_lshl_add_u64 v[30:31], s[6:7], 1, v[26:27]
	v_lshl_add_u64 v[30:31], v[30:31], 0, v[148:149]
	v_cvt_pk_bf16_f32 v12, v12, v13
	v_cvt_pk_bf16_f32 v13, v14, v15
	v_cvt_pk_bf16_f32 v8, v8, v9
	v_cvt_pk_bf16_f32 v9, v10, v11
	global_store_dwordx2 v[30:31], v[12:13], off
	global_store_dwordx2 v[30:31], v[8:9], off offset:64
	s_and_b64 vcc, exec, s[8:9]
	s_cbranch_vccz .LBB0_956

.LBB0_956:
	s_waitcnt vmcnt(0)
	v_mov_b32_e32 v8, v16
	v_mul_f32_e32 v14, v2, v21
	v_mul_f32_e32 v16, v2, v20
	v_mov_b32_e32 v2, v7
	v_mov_b32_e32 v9, v18
	v_mov_b32_e32 v18, v17
	v_mul_f32_e32 v12, v6, v20
	v_mul_f32_e32 v20, v6, v21
	v_mul_f32_e32 v30, v2, v22
	v_mul_f32_e32 v31, v3, v23
	v_mov_b32_e32 v6, v3
	v_mul_f32_e32 v10, v0, v18
	v_mul_f32_e32 v11, v1, v19
	v_mov_b32_e32 v13, v30
	v_mov_b32_e32 v15, v31
	v_mul_f32_e32 v2, v6, v22
	v_mul_f32_e32 v3, v7, v23
	v_mul_f32_e32 v0, v0, v8
	v_mul_f32_e32 v1, v1, v9
	v_fma_f32 v8, v4, v8, -v10
	v_fma_f32 v9, v5, v9, -v11
	v_sub_f32_e32 v10, v12, v14
	v_sub_f32_e32 v11, v13, v15
	v_mov_b32_e32 v21, v3
	v_mov_b32_e32 v17, v2
	v_fma_f32 v0, v4, v18, v0
	v_fma_f32 v1, v5, v19, v1
	v_add_f32_e32 v2, v20, v16
	v_add_f32_e32 v3, v21, v17
	v_mov_b32_e32 v4, v8
	v_mov_b32_e32 v5, v9
	v_mov_b32_e32 v6, v10
	v_mov_b32_e32 v7, v11
	s_and_b64 vcc, exec, s[10:11]
	s_cbranch_vccz .LBB0_935

.LBB0_959:
	s_ashr_i32 s7, s6, 31
	v_mul_f32_e32 v6, s60, v6
	v_mul_f32_e32 v7, s60, v7
	v_mul_f32_e32 v4, s60, v4
	v_mul_f32_e32 v5, s60, v5
	v_mul_f32_e32 v2, s60, v2
	v_mul_f32_e32 v3, s60, v3
	v_mul_f32_e32 v0, s60, v0
	v_mul_f32_e32 v1, s60, v1
	v_lshl_add_u64 v[8:9], s[6:7], 1, v[26:27]
	v_lshl_add_u64 v[8:9], v[8:9], 0, v[148:149]
	v_cvt_pk_bf16_f32 v4, v4, v5
	v_cvt_pk_bf16_f32 v5, v6, v7
	v_cvt_pk_bf16_f32 v0, v0, v1
	v_cvt_pk_bf16_f32 v1, v2, v3
	global_store_dwordx2 v[8:9], v[4:5], off
	global_store_dwordx2 v[8:9], v[0:1], off offset:64

.LBB0_967:
	s_ashr_i32 s9, s8, 31
	v_mul_f32_e32 v110, s60, v110
	v_mul_f32_e32 v111, s60, v111
	v_mul_f32_e32 v108, s60, v108
	v_mul_f32_e32 v109, s60, v109
	v_mul_f32_e32 v106, s60, v106
	v_mul_f32_e32 v107, s60, v107
	v_mul_f32_e32 v104, s60, v104
	v_mul_f32_e32 v105, s60, v105
	v_lshl_add_u64 v[126:127], s[8:9], 1, v[122:123]
	v_lshl_add_u64 v[126:127], v[126:127], 0, v[148:149]
	v_cvt_pk_bf16_f32 v108, v108, v109
	v_cvt_pk_bf16_f32 v109, v110, v111
	v_cvt_pk_bf16_f32 v104, v104, v105
	v_cvt_pk_bf16_f32 v105, v106, v107
	global_store_dwordx2 v[126:127], v[108:109], off
	global_store_dwordx2 v[126:127], v[104:105], off offset:64
	v_cndmask_b32_e64 v104, 0, 1, s[10:11]
	v_cmp_ne_u32_e64 s[8:9], 1, v104
	s_andn2_b64 vcc, exec, s[10:11]
	s_cbranch_vccz .LBB0_765

.LBB0_993:
	s_ashr_i32 s73, s72, 31
	v_mul_f32_e32 v94, s60, v94
	v_mul_f32_e32 v95, s60, v95
	v_mul_f32_e32 v92, s60, v92
	v_mul_f32_e32 v93, s60, v93
	v_mul_f32_e32 v90, s60, v90
	v_mul_f32_e32 v91, s60, v91
	v_mul_f32_e32 v88, s60, v88
	v_mul_f32_e32 v89, s60, v89
	v_lshl_add_u64 v[110:111], s[72:73], 1, v[106:107]
	v_lshl_add_u64 v[110:111], v[110:111], 0, v[148:149]
	v_cvt_pk_bf16_f32 v92, v92, v93
	v_cvt_pk_bf16_f32 v93, v94, v95
	v_cvt_pk_bf16_f32 v88, v88, v89
	v_cvt_pk_bf16_f32 v89, v90, v91
	global_store_dwordx2 v[110:111], v[92:93], off
	global_store_dwordx2 v[110:111], v[88:89], off offset:64
	s_and_b64 vcc, exec, s[8:9]
	s_cbranch_vccz .LBB0_793

.LBB0_1019:
	s_ashr_i32 s73, s72, 31
	v_mul_f32_e32 v78, s60, v78
	v_mul_f32_e32 v79, s60, v79
	v_mul_f32_e32 v76, s60, v76
	v_mul_f32_e32 v77, s60, v77
	v_mul_f32_e32 v74, s60, v74
	v_mul_f32_e32 v75, s60, v75
	v_mul_f32_e32 v72, s60, v72
	v_mul_f32_e32 v73, s60, v73
	v_lshl_add_u64 v[94:95], s[72:73], 1, v[90:91]
	v_lshl_add_u64 v[94:95], v[94:95], 0, v[148:149]
	v_cvt_pk_bf16_f32 v76, v76, v77
	v_cvt_pk_bf16_f32 v77, v78, v79
	v_cvt_pk_bf16_f32 v72, v72, v73
	v_cvt_pk_bf16_f32 v73, v74, v75
	global_store_dwordx2 v[94:95], v[76:77], off
	global_store_dwordx2 v[94:95], v[72:73], off offset:64
	s_and_b64 vcc, exec, s[8:9]
	s_cbranch_vccz .LBB0_821

.LBB0_1045:
	s_ashr_i32 s73, s72, 31
	v_mul_f32_e32 v62, s60, v62
	v_mul_f32_e32 v63, s60, v63
	v_mul_f32_e32 v60, s60, v60
	v_mul_f32_e32 v61, s60, v61
	v_mul_f32_e32 v58, s60, v58
	v_mul_f32_e32 v59, s60, v59
	v_mul_f32_e32 v56, s60, v56
	v_mul_f32_e32 v57, s60, v57
	v_lshl_add_u64 v[78:79], s[72:73], 1, v[74:75]
	v_lshl_add_u64 v[78:79], v[78:79], 0, v[148:149]
	v_cvt_pk_bf16_f32 v60, v60, v61
	v_cvt_pk_bf16_f32 v61, v62, v63
	v_cvt_pk_bf16_f32 v56, v56, v57
	v_cvt_pk_bf16_f32 v57, v58, v59
	global_store_dwordx2 v[78:79], v[60:61], off
	global_store_dwordx2 v[78:79], v[56:57], off offset:64
	s_and_b64 vcc, exec, s[8:9]
	s_cbranch_vccz .LBB0_849

.LBB0_1071:
	s_ashr_i32 s73, s72, 31
	v_mul_f32_e32 v46, s60, v46
	v_mul_f32_e32 v47, s60, v47
	v_mul_f32_e32 v44, s60, v44
	v_mul_f32_e32 v45, s60, v45
	v_mul_f32_e32 v42, s60, v42
	v_mul_f32_e32 v43, s60, v43
	v_mul_f32_e32 v40, s60, v40
	v_mul_f32_e32 v41, s60, v41
	v_lshl_add_u64 v[62:63], s[72:73], 1, v[58:59]
	v_lshl_add_u64 v[62:63], v[62:63], 0, v[148:149]
	v_cvt_pk_bf16_f32 v44, v44, v45
	v_cvt_pk_bf16_f32 v45, v46, v47
	v_cvt_pk_bf16_f32 v40, v40, v41
	v_cvt_pk_bf16_f32 v41, v42, v43
	global_store_dwordx2 v[62:63], v[44:45], off
	global_store_dwordx2 v[62:63], v[40:41], off offset:64
	s_and_b64 vcc, exec, s[8:9]
	s_cbranch_vccz .LBB0_877

.LBB0_1097:
	s_ashr_i32 s73, s72, 31
	v_mul_f32_e32 v30, s60, v30
	v_mul_f32_e32 v31, s60, v31
	v_mul_f32_e32 v28, s60, v28
	v_mul_f32_e32 v29, s60, v29
	v_mul_f32_e32 v26, s60, v26
	v_mul_f32_e32 v27, s60, v27
	v_mul_f32_e32 v24, s60, v24
	v_mul_f32_e32 v25, s60, v25
	v_lshl_add_u64 v[46:47], s[72:73], 1, v[42:43]
	v_lshl_add_u64 v[46:47], v[46:47], 0, v[148:149]
	v_cvt_pk_bf16_f32 v28, v28, v29
	v_cvt_pk_bf16_f32 v29, v30, v31
	v_cvt_pk_bf16_f32 v24, v24, v25
	v_cvt_pk_bf16_f32 v25, v26, v27
	global_store_dwordx2 v[46:47], v[28:29], off
	global_store_dwordx2 v[46:47], v[24:25], off offset:64
	s_and_b64 vcc, exec, s[8:9]
	s_cbranch_vccz .LBB0_905
